# merge<4>: the 16 gate loads of each branch epilogue issued together instead of 16 dependent round trips
# speedup vs baseline: 1.0169x; 1.0169x over previous
.LBB0_2032:
	s_load_dwordx2 s[10:11], s[0:1], 0x198
	s_lshl_b32 s20, s19, 11
	s_waitcnt lgkmcnt(0)
	s_add_u32 s10, s10, s20
	s_addc_u32 s11, s11, 0
	v_lshl_add_u64 v[152:153], v[86:87], 1, s[10:11]
	v_lshl_add_u64 v[154:155], v[152:153], 0, v[104:105]
	v_lshl_add_u64 v[156:157], v[152:153], 0, v[110:111]
	v_lshl_add_u64 v[158:159], v[152:153], 0, v[112:113]
	v_lshl_add_u64 v[242:243], v[152:153], 0, v[118:119]
	global_load_dwordx2 v[206:207], v[154:155], off
	global_load_dwordx2 v[208:209], v[154:155], off offset:32
	global_load_dwordx2 v[210:211], v[154:155], off offset:64
	global_load_dwordx2 v[212:213], v[154:155], off offset:96
	global_load_dwordx2 v[214:215], v[156:157], off
	global_load_dwordx2 v[216:217], v[156:157], off offset:32
	global_load_dwordx2 v[218:219], v[156:157], off offset:64
	global_load_dwordx2 v[220:221], v[156:157], off offset:96
	global_load_dwordx2 v[222:223], v[158:159], off
	global_load_dwordx2 v[224:225], v[158:159], off offset:32
	global_load_dwordx2 v[226:227], v[158:159], off offset:64
	global_load_dwordx2 v[228:229], v[158:159], off offset:96
	global_load_dwordx2 v[230:231], v[242:243], off
	global_load_dwordx2 v[232:233], v[242:243], off offset:32
	global_load_dwordx2 v[234:235], v[242:243], off offset:64
	global_load_dwordx2 v[236:237], v[242:243], off offset:96
	s_add_i32 s19, s19, 1
	s_cmp_eq_u32 s19, 3
	s_waitcnt vmcnt(15)
	v_lshlrev_b32_e32 v238, 16, v206
	v_and_b32_e32 v239, 0xffff0000, v206
	v_lshlrev_b32_e32 v240, 16, v207
	v_and_b32_e32 v241, 0xffff0000, v207
	v_pk_fma_f32 v[148:149], v[62:63], v[238:239], v[148:149]
	v_pk_fma_f32 v[150:151], v[64:65], v[240:241], v[150:151]
	s_waitcnt vmcnt(14)
	v_lshlrev_b32_e32 v238, 16, v208
	v_and_b32_e32 v239, 0xffff0000, v208
	v_lshlrev_b32_e32 v240, 16, v209
	v_and_b32_e32 v241, 0xffff0000, v209
	v_pk_fma_f32 v[146:147], v[58:59], v[238:239], v[146:147]
	v_pk_fma_f32 v[144:145], v[60:61], v[240:241], v[144:145]
	s_waitcnt vmcnt(13)
	v_lshlrev_b32_e32 v238, 16, v210
	v_and_b32_e32 v239, 0xffff0000, v210
	v_lshlrev_b32_e32 v240, 16, v211
	v_and_b32_e32 v241, 0xffff0000, v211
	v_pk_fma_f32 v[140:141], v[54:55], v[238:239], v[140:141]
	v_pk_fma_f32 v[142:143], v[56:57], v[240:241], v[142:143]
	s_waitcnt vmcnt(12)
	v_lshlrev_b32_e32 v238, 16, v212
	v_and_b32_e32 v239, 0xffff0000, v212
	v_lshlrev_b32_e32 v240, 16, v213
	v_and_b32_e32 v241, 0xffff0000, v213
	v_pk_fma_f32 v[136:137], v[50:51], v[238:239], v[136:137]
	v_pk_fma_f32 v[138:139], v[52:53], v[240:241], v[138:139]
	s_waitcnt vmcnt(11)
	v_lshlrev_b32_e32 v238, 16, v214
	v_and_b32_e32 v239, 0xffff0000, v214
	v_lshlrev_b32_e32 v240, 16, v215
	v_and_b32_e32 v241, 0xffff0000, v215
	v_pk_fma_f32 v[128:129], v[46:47], v[238:239], v[128:129]
	v_pk_fma_f32 v[130:131], v[48:49], v[240:241], v[130:131]
	s_waitcnt vmcnt(10)
	v_lshlrev_b32_e32 v238, 16, v216
	v_and_b32_e32 v239, 0xffff0000, v216
	v_lshlrev_b32_e32 v240, 16, v217
	v_and_b32_e32 v241, 0xffff0000, v217
	v_pk_fma_f32 v[124:125], v[42:43], v[238:239], v[124:125]
	v_pk_fma_f32 v[126:127], v[44:45], v[240:241], v[126:127]
	s_waitcnt vmcnt(9)
	v_lshlrev_b32_e32 v238, 16, v218
	v_and_b32_e32 v239, 0xffff0000, v218
	v_lshlrev_b32_e32 v240, 16, v219
	v_and_b32_e32 v241, 0xffff0000, v219
	v_pk_fma_f32 v[120:121], v[38:39], v[238:239], v[120:121]
	v_pk_fma_f32 v[122:123], v[40:41], v[240:241], v[122:123]
	s_waitcnt vmcnt(8)
	v_lshlrev_b32_e32 v238, 16, v220
	v_and_b32_e32 v239, 0xffff0000, v220
	v_lshlrev_b32_e32 v240, 16, v221
	v_and_b32_e32 v241, 0xffff0000, v221
	v_pk_fma_f32 v[114:115], v[34:35], v[238:239], v[114:115]
	v_pk_fma_f32 v[116:117], v[36:37], v[240:241], v[116:117]
	s_waitcnt vmcnt(7)
	v_lshlrev_b32_e32 v238, 16, v222
	v_and_b32_e32 v239, 0xffff0000, v222
	v_lshlrev_b32_e32 v240, 16, v223
	v_and_b32_e32 v241, 0xffff0000, v223
	v_pk_fma_f32 v[106:107], v[30:31], v[238:239], v[106:107]
	v_pk_fma_f32 v[108:109], v[32:33], v[240:241], v[108:109]
	s_waitcnt vmcnt(6)
	v_lshlrev_b32_e32 v238, 16, v224
	v_and_b32_e32 v239, 0xffff0000, v224
	v_lshlrev_b32_e32 v240, 16, v225
	v_and_b32_e32 v241, 0xffff0000, v225
	v_pk_fma_f32 v[100:101], v[26:27], v[238:239], v[100:101]
	v_pk_fma_f32 v[102:103], v[28:29], v[240:241], v[102:103]
	s_waitcnt vmcnt(5)
	v_lshlrev_b32_e32 v238, 16, v226
	v_and_b32_e32 v239, 0xffff0000, v226
	v_lshlrev_b32_e32 v240, 16, v227
	v_and_b32_e32 v241, 0xffff0000, v227
	v_pk_fma_f32 v[96:97], v[22:23], v[238:239], v[96:97]
	v_pk_fma_f32 v[98:99], v[24:25], v[240:241], v[98:99]
	s_waitcnt vmcnt(4)
	v_lshlrev_b32_e32 v238, 16, v228
	v_and_b32_e32 v239, 0xffff0000, v228
	v_lshlrev_b32_e32 v240, 16, v229
	v_and_b32_e32 v241, 0xffff0000, v229
	v_pk_fma_f32 v[90:91], v[18:19], v[238:239], v[90:91]
	v_pk_fma_f32 v[92:93], v[20:21], v[240:241], v[92:93]
	s_waitcnt vmcnt(3)
	v_lshlrev_b32_e32 v238, 16, v230
	v_and_b32_e32 v239, 0xffff0000, v230
	v_lshlrev_b32_e32 v240, 16, v231
	v_and_b32_e32 v241, 0xffff0000, v231
	v_pk_fma_f32 v[82:83], v[14:15], v[238:239], v[82:83]
	v_pk_fma_f32 v[84:85], v[16:17], v[240:241], v[84:85]
	s_waitcnt vmcnt(2)
	v_lshlrev_b32_e32 v238, 16, v232
	v_and_b32_e32 v239, 0xffff0000, v232
	v_lshlrev_b32_e32 v240, 16, v233
	v_and_b32_e32 v241, 0xffff0000, v233
	v_pk_fma_f32 v[76:77], v[10:11], v[238:239], v[76:77]
	v_pk_fma_f32 v[78:79], v[12:13], v[240:241], v[78:79]
	s_waitcnt vmcnt(1)
	v_lshlrev_b32_e32 v238, 16, v234
	v_and_b32_e32 v239, 0xffff0000, v234
	v_lshlrev_b32_e32 v240, 16, v235
	v_and_b32_e32 v241, 0xffff0000, v235
	v_pk_fma_f32 v[72:73], v[6:7], v[238:239], v[72:73]
	v_pk_fma_f32 v[74:75], v[8:9], v[240:241], v[74:75]
	s_waitcnt vmcnt(0)
	v_lshlrev_b32_e32 v238, 16, v236
	v_and_b32_e32 v239, 0xffff0000, v236
	v_lshlrev_b32_e32 v240, 16, v237
	v_and_b32_e32 v241, 0xffff0000, v237
	v_pk_fma_f32 v[66:67], v[2:3], v[238:239], v[66:67]
	v_pk_fma_f32 v[68:69], v[4:5], v[240:241], v[68:69]
	s_cbranch_scc1 .LBB0_2030
